# v37 + group-barrier L1 invalidate (buffer_inv sc1) issued before the arrive atomic/poll so it overlaps the wait (block is quiescent during poll)
# speedup vs baseline: 1.0028x; 1.0028x over previous
.Lgb4:
	buffer_inv sc1
	s_and_b32 s2, s3, 63
	s_lshl_b32 s2, s2, 2
	s_add_u32 s8, s22, 0x1be4c200
	s_addc_u32 s9, s23, 0
	s_add_u32 s8, s8, s2
	s_addc_u32 s9, s9, 0
	v_mov_b32_e32 v0, 0
	v_mov_b32_e32 v1, 1
	global_atomic_add v0, v1, s[8:9]
	s_lshl_b32 s2, s32, 2
	s_add_i32 s2, s2, -4
	s_mov_b32 s10, 0
.Lgb4_poll:
	global_load_dword v2, v0, s[8:9] sc1
	s_add_i32 s10, s10, 1
	s_waitcnt vmcnt(0)
	v_cmp_gt_u32_e32 vcc, s2, v2
	s_cmp_lt_u32 s10, 0x4000
	s_cselect_b64 s[12:13], -1, 0
	s_and_b64 vcc, vcc, s[12:13]
	s_cbranch_vccnz .Lgb4_poll
	s_add_u32 s12, s22, 0x1be4c400
	s_addc_u32 s13, s23, 0
	global_atomic_add v0, v1, s[12:13]
	s_waitcnt vmcnt(0)

.Lgb5_poll:
	global_load_dword v2, v0, s[8:9] sc1
	s_add_i32 s10, s10, 1
	s_waitcnt vmcnt(0)
	v_cmp_gt_u32_e32 vcc, s2, v2
	s_cmp_lt_u32 s10, 0x4000
	s_cselect_b64 s[12:13], -1, 0
	s_and_b64 vcc, vcc, s[12:13]
	s_cbranch_vccnz .Lgb5_poll
	s_waitcnt vmcnt(0)

.Lp4done_poll:
	global_load_dword v2, v0, s[12:13] sc1
	s_add_i32 s10, s10, 1
	s_waitcnt vmcnt(0)
	v_cmp_gt_u32_e32 vcc, 0x100, v2
	s_cmp_lt_u32 s10, 0x4000
	s_cselect_b64 s[14:15], -1, 0
	s_and_b64 vcc, vcc, s[14:15]
	s_cbranch_vccnz .Lp4done_poll
	s_waitcnt vmcnt(0)
